# mLSTM seg_pass fill block: all 16+3 loads issued up front (was one load per s_waitcnt vmcnt(0)); norm_rows loops: loop-invariant norm weights preloaded (no per-row reload/wait); on top of pipelined re
# speedup vs baseline: 1.0053x; 1.0053x over previous
.LBB0_81:
	s_or_b64 exec, exec, s[4:5]
	s_cmpk_gt_i32 s46, 0x3fff
	s_cbranch_scc1 .LBB0_85
	v_mbcnt_lo_u32_b32 v0, -1, 0
	v_mbcnt_hi_u32_b32 v0, -1, v0
	v_and_b32_e32 v1, 64, v0
	v_add_u32_e32 v1, 64, v1
	v_xor_b32_e32 v2, 1, v0
	v_cmp_lt_i32_e32 vcc, v2, v1
	v_readlane_b32 s0, v255, 7
	v_readlane_b32 s14, v255, 21
	v_cndmask_b32_e32 v2, v0, v2, vcc
	v_lshlrev_b32_e32 v26, 2, v2
	v_xor_b32_e32 v2, 2, v0
	v_cmp_lt_i32_e32 vcc, v2, v1
	v_readlane_b32 s15, v255, 22
	v_readlane_b32 s4, v255, 11
	v_cndmask_b32_e32 v2, v0, v2, vcc
	v_lshlrev_b32_e32 v27, 2, v2
	v_xor_b32_e32 v2, 4, v0
	v_cmp_lt_i32_e32 vcc, v2, v1
	v_readlane_b32 s5, v255, 12
	v_readlane_b32 s6, v255, 13
	v_cndmask_b32_e32 v2, v0, v2, vcc
	v_lshlrev_b32_e32 v28, 2, v2
	v_xor_b32_e32 v2, 8, v0
	v_cmp_lt_i32_e32 vcc, v2, v1
	v_readlane_b32 s7, v255, 14
	v_readlane_b32 s8, v255, 15
	v_cndmask_b32_e32 v2, v0, v2, vcc
	v_lshlrev_b32_e32 v29, 2, v2
	v_xor_b32_e32 v2, 16, v0
	v_cmp_lt_i32_e32 vcc, v2, v1
	v_readlane_b32 s9, v255, 16
	v_readlane_b32 s10, v255, 17
	v_cndmask_b32_e32 v2, v0, v2, vcc
	v_lshlrev_b32_e32 v30, 2, v2
	v_xor_b32_e32 v2, 32, v0
	v_cmp_lt_i32_e32 vcc, v2, v1
	v_readlane_b32 s11, v255, 18
	v_readlane_b32 s12, v255, 19
	v_cndmask_b32_e32 v0, v0, v2, vcc
	v_readlane_b32 s13, v255, 20
	s_mov_b64 s[58:59], s[14:15]
	v_lshlrev_b32_e32 v31, 2, v0
	v_lshlrev_b32_e32 v0, 4, v130
	v_mov_b32_e32 v1, 0
	v_readlane_b32 s2, v255, 9
	v_readlane_b32 s3, v255, 10
	s_mov_b64 s[48:49], s[4:5]
	v_lshl_add_u64 v[12:13], s[48:49], 0, v[0:1]
	s_mov_b64 s[2:3], 0x1400
	v_lshl_add_u64 v[16:17], v[12:13], 0, s[2:3]
	s_mov_b64 s[2:3], 0x1800
	v_readlane_b32 s1, v255, 8
	v_lshl_add_u64 v[18:19], v[12:13], 0, s[2:3]
	s_mov_b64 s[2:3], 0x1c00
	s_ashr_i32 s47, s46, 31
	s_mov_b64 s[44:45], s[0:1]
	v_lshl_add_u64 v[20:21], v[12:13], 0, s[2:3]
	s_lshl_b64 s[2:3], s[46:47], 13
	s_mov_b64 s[56:57], s[12:13]
	s_mov_b64 s[54:55], s[10:11]
	s_mov_b64 s[52:53], s[8:9]
	s_mov_b64 s[50:51], s[6:7]
	s_add_u32 s2, s44, s2
	v_readlane_b32 s8, v255, 23
	s_addc_u32 s3, s45, s3
	v_readlane_b32 s9, v255, 24
	s_mov_b64 s[0:1], 0x1000
	v_lshl_add_u64 v[2:3], s[2:3], 0, v[0:1]
	s_ashr_i32 s9, s8, 31
	v_lshl_add_u64 v[14:15], v[12:13], 0, s[0:1]
	v_lshl_add_u64 v[22:23], v[2:3], 0, s[0:1]
	s_lshl_b64 s[2:3], s[8:9], 13
	s_lshl_b64 s[0:1], s[46:47], 12
	s_add_u32 s0, s80, s0
	v_lshlrev_b32_e32 v0, 3, v130
	s_addc_u32 s1, s81, s1
	v_lshl_add_u64 v[0:1], s[0:1], 0, v[0:1]
	s_mov_b64 s[0:1], 0xa200000
	v_lshl_add_u64 v[24:25], v[0:1], 0, s[0:1]
	s_lshl_b64 s[4:5], s[8:9], 12
	v_mov_b32_e32 v32, 0x358637bd
	s_mov_b32 s6, 0xf800000
	v_mov_b32_e32 v33, 0x260
	s_mov_b32 s7, s46
	global_load_dwordx4 v[132:135], v[12:13], off offset:1024
	global_load_dwordx4 v[136:139], v[12:13], off offset:2048
	global_load_dwordx4 v[140:143], v[12:13], off offset:3072
	global_load_dwordx4 v[144:147], v[14:15], off
	global_load_dwordx4 v[148:151], v[16:17], off
	global_load_dwordx4 v[152:155], v[18:19], off
	global_load_dwordx4 v[156:159], v[20:21], off
.LBB0_83:
	global_load_dwordx4 v[34:37], v[22:23], off offset:-4096
	global_load_dwordx4 v[8:11], v[22:23], off offset:-3072
	global_load_dwordx4 v[38:41], v[22:23], off offset:-2048
	global_load_dwordx4 v[4:7], v[22:23], off
	global_load_dwordx4 v[42:45], v[22:23], off offset:-1024
	global_load_dwordx4 v[46:49], v[22:23], off offset:1024
	global_load_dwordx4 v[0:3], v[22:23], off offset:3072
	global_load_dwordx4 v[50:53], v[22:23], off offset:2048
	global_load_dwordx4 v[54:57], v[12:13], off
	s_add_i32 s7, s7, s8
	v_lshl_add_u64 v[22:23], v[22:23], 0, s[2:3]
	s_cmpk_lt_i32 s7, 0x4000
	s_waitcnt vmcnt(8)
	v_mov_b32_e32 v60, v35
	s_waitcnt vmcnt(7)
	v_mov_b32_e32 v61, v9
	v_mov_b32_e32 v64, v37
	v_mov_b32_e32 v65, v11
	v_mov_b32_e32 v58, v34
	v_mov_b32_e32 v59, v8
	v_mov_b32_e32 v62, v36
	v_mov_b32_e32 v63, v10
	s_waitcnt vmcnt(6)
	v_pk_mul_f32 v[66:67], v[40:41], v[40:41]
	v_pk_mul_f32 v[68:69], v[38:39], v[38:39]
	v_pk_mul_f32 v[60:61], v[60:61], v[60:61]
	v_pk_mul_f32 v[64:65], v[64:65], v[64:65]
	v_pk_mov_b32 v[82:83], v[68:69], v[66:67] op_sel:[1,0]
	v_mov_b32_e32 v69, v67
	v_pk_fma_f32 v[58:59], v[58:59], v[58:59], v[60:61]
	v_pk_fma_f32 v[60:61], v[62:63], v[62:63], v[64:65]
	s_waitcnt vmcnt(4)
	v_mul_f32_e32 v70, v43, v43
	v_mul_f32_e32 v72, v45, v45
	v_pk_add_f32 v[62:63], v[82:83], v[68:69]
	v_pk_add_f32 v[58:59], v[58:59], v[60:61]
	v_mul_f32_e32 v81, v4, v4
	v_mul_f32_e32 v84, v5, v5
	v_mul_f32_e32 v85, v6, v6
	v_mul_f32_e32 v86, v7, v7
	v_pk_fma_f32 v[66:67], v[42:43], v[42:43], v[70:71] op_sel_hi:[1,1,0]
	v_pk_fma_f32 v[70:71], v[44:45], v[44:45], v[72:73] op_sel_hi:[1,1,0]
	v_pk_add_f32 v[60:61], v[62:63], v[62:63] op_sel:[0,1] op_sel_hi:[1,0]
	v_pk_add_f32 v[58:59], v[58:59], v[58:59] op_sel:[0,1] op_sel_hi:[1,0]
	s_waitcnt vmcnt(3)
	v_pk_mul_f32 v[74:75], v[48:49], v[48:49]
	v_pk_mul_f32 v[76:77], v[46:47], v[46:47]
	v_mov_b32_e32 v67, v85
	v_mov_b32_e32 v71, v86
	v_mov_b32_e32 v61, v84
	v_mov_b32_e32 v59, v81
	v_pk_mov_b32 v[72:73], v[76:77], v[74:75] op_sel:[1,0]
	v_mov_b32_e32 v77, v75
	v_pk_add_f32 v[62:63], v[66:67], v[70:71]
	v_pk_add_f32 v[58:59], v[58:59], v[60:61]
	s_waitcnt vmcnt(1)
	v_mul_f32_e32 v78, v51, v51
	v_mul_f32_e32 v80, v53, v53
	v_pk_add_f32 v[64:65], v[72:73], v[76:77]
	v_pk_add_f32 v[58:59], v[58:59], v[62:63]
	v_mul_f32_e32 v87, v0, v0
	v_mul_f32_e32 v88, v1, v1
	v_mul_f32_e32 v89, v2, v2
	v_mul_f32_e32 v90, v3, v3
	v_pk_fma_f32 v[74:75], v[50:51], v[50:51], v[78:79] op_sel_hi:[1,1,0]
	v_pk_fma_f32 v[78:79], v[52:53], v[52:53], v[80:81] op_sel_hi:[1,1,0]
	v_pk_add_f32 v[64:65], v[64:65], v[64:65] op_sel:[0,1] op_sel_hi:[1,0]
	v_pk_add_f32 v[58:59], v[58:59], v[58:59] op_sel:[0,1] op_sel_hi:[1,0]
	v_mov_b32_e32 v75, v89
	v_mov_b32_e32 v79, v90
	v_mov_b32_e32 v65, v88
	v_mov_b32_e32 v59, v87
	v_pk_add_f32 v[66:67], v[74:75], v[78:79]
	v_pk_add_f32 v[58:59], v[58:59], v[64:65]
	s_nop 0
	v_pk_add_f32 v[58:59], v[58:59], v[66:67]
	s_nop 0
	v_add_f32_e32 v58, v58, v59
	ds_bpermute_b32 v59, v26, v58
	s_waitcnt lgkmcnt(0)
	v_add_f32_e32 v58, v58, v59
	ds_bpermute_b32 v59, v27, v58
	s_waitcnt lgkmcnt(0)
	v_add_f32_e32 v58, v58, v59
	ds_bpermute_b32 v59, v28, v58
	s_waitcnt lgkmcnt(0)
	v_add_f32_e32 v58, v58, v59
	ds_bpermute_b32 v59, v29, v58
	s_waitcnt lgkmcnt(0)
	v_add_f32_e32 v58, v58, v59
	ds_bpermute_b32 v59, v30, v58
	s_waitcnt lgkmcnt(0)
	v_add_f32_e32 v58, v58, v59
	ds_bpermute_b32 v59, v31, v58
	s_waitcnt lgkmcnt(0)
	v_add_f32_e32 v58, v58, v59
	v_fmamk_f32 v58, v58, 0x3a000000, v32
	v_mul_f32_e32 v59, 0x4f800000, v58
	v_cmp_gt_f32_e32 vcc, s6, v58
	s_nop 1
	v_cndmask_b32_e32 v58, v58, v59, vcc
	v_sqrt_f32_e32 v59, v58
	s_nop 0
	v_add_u32_e32 v60, -1, v59
	v_add_u32_e32 v61, 1, v59
	v_fma_f32 v62, -v60, v59, v58
	v_fma_f32 v63, -v61, v59, v58
	v_cmp_ge_f32_e64 s[0:1], 0, v62
	s_nop 1
	v_cndmask_b32_e64 v59, v59, v60, s[0:1]
	v_cmp_lt_f32_e64 s[0:1], 0, v63
	s_nop 1
	v_cndmask_b32_e64 v59, v59, v61, s[0:1]
	v_mul_f32_e32 v60, 0x37800000, v59
	v_cndmask_b32_e32 v59, v59, v60, vcc
	v_cmp_class_f32_e32 vcc, v58, v33
	s_nop 1
	v_cndmask_b32_e32 v58, v59, v58, vcc
	v_div_scale_f32 v59, s[0:1], v58, v58, 1.0
	v_rcp_f32_e32 v61, v59
	v_div_scale_f32 v60, vcc, 1.0, v58, 1.0
	v_fma_f32 v62, -v59, v61, 1.0
	v_fmac_f32_e32 v61, v62, v61
	v_mul_f32_e32 v62, v60, v61
	v_fma_f32 v63, -v59, v62, v60
	v_fmac_f32_e32 v62, v63, v61
	v_fma_f32 v59, -v59, v62, v60
	v_div_fmas_f32 v59, v59, v61, v62
	v_div_fixup_f32 v58, v59, v58, 1.0
	v_pk_mul_f32 v[34:35], v[34:35], v[58:59] op_sel_hi:[1,0]
	v_pk_mul_f32 v[36:37], v[36:37], v[58:59] op_sel_hi:[1,0]
	s_waitcnt vmcnt(0)
	v_pk_mul_f32 v[34:35], v[54:55], v[34:35]
	v_pk_mul_f32 v[36:37], v[56:57], v[36:37]
	v_cvt_pk_bf16_f32 v34, v34, v35
	v_cvt_pk_bf16_f32 v35, v36, v37
	global_store_dwordx2 v[24:25], v[34:35], off
	v_pk_mul_f32 v[8:9], v[8:9], v[58:59] op_sel_hi:[1,0]
	v_pk_mul_f32 v[10:11], v[10:11], v[58:59] op_sel_hi:[1,0]
	v_pk_mul_f32 v[4:5], v[4:5], v[58:59] op_sel_hi:[1,0]
	v_pk_mul_f32 v[6:7], v[6:7], v[58:59] op_sel_hi:[1,0]
	v_pk_mul_f32 v[0:1], v[0:1], v[58:59] op_sel_hi:[1,0]
	v_pk_mul_f32 v[2:3], v[2:3], v[58:59] op_sel_hi:[1,0]
	v_pk_mul_f32 v[10:11], v[134:135], v[10:11]
	v_pk_mul_f32 v[8:9], v[132:133], v[8:9]
	v_pk_mul_f32 v[34:35], v[38:39], v[58:59] op_sel_hi:[1,0]
	v_cvt_pk_bf16_f32 v8, v8, v9
	v_cvt_pk_bf16_f32 v9, v10, v11
	global_store_dwordx2 v[24:25], v[8:9], off offset:512
	v_pk_mul_f32 v[36:37], v[40:41], v[58:59] op_sel_hi:[1,0]
	v_pk_mul_f32 v[8:9], v[136:137], v[34:35]
	v_pk_mul_f32 v[10:11], v[138:139], v[36:37]
	v_cvt_pk_bf16_f32 v8, v8, v9
	v_cvt_pk_bf16_f32 v9, v10, v11
	global_store_dwordx2 v[24:25], v[8:9], off offset:1024
	v_pk_mul_f32 v[34:35], v[42:43], v[58:59] op_sel_hi:[1,0]
	v_pk_mul_f32 v[36:37], v[44:45], v[58:59] op_sel_hi:[1,0]
	v_pk_mul_f32 v[8:9], v[140:141], v[34:35]
	v_pk_mul_f32 v[10:11], v[142:143], v[36:37]
	v_cvt_pk_bf16_f32 v8, v8, v9
	v_cvt_pk_bf16_f32 v9, v10, v11
	global_store_dwordx2 v[24:25], v[8:9], off offset:1536
	v_pk_mul_f32 v[6:7], v[146:147], v[6:7]
	v_pk_mul_f32 v[4:5], v[144:145], v[4:5]
	v_pk_mul_f32 v[8:9], v[46:47], v[58:59] op_sel_hi:[1,0]
	v_cvt_pk_bf16_f32 v4, v4, v5
	v_cvt_pk_bf16_f32 v5, v6, v7
	global_store_dwordx2 v[24:25], v[4:5], off offset:2048
	v_pk_mul_f32 v[10:11], v[48:49], v[58:59] op_sel_hi:[1,0]
	v_pk_mul_f32 v[4:5], v[148:149], v[8:9]
	v_pk_mul_f32 v[6:7], v[150:151], v[10:11]
	v_cvt_pk_bf16_f32 v4, v4, v5
	v_cvt_pk_bf16_f32 v5, v6, v7
	global_store_dwordx2 v[24:25], v[4:5], off offset:2560
	v_pk_mul_f32 v[8:9], v[50:51], v[58:59] op_sel_hi:[1,0]
	v_pk_mul_f32 v[10:11], v[52:53], v[58:59] op_sel_hi:[1,0]
	v_pk_mul_f32 v[4:5], v[8:9], v[152:153]
	v_pk_mul_f32 v[6:7], v[10:11], v[154:155]
	v_cvt_pk_bf16_f32 v4, v4, v5
	v_cvt_pk_bf16_f32 v5, v6, v7
	global_store_dwordx2 v[24:25], v[4:5], off offset:3072
	v_pk_mul_f32 v[2:3], v[2:3], v[158:159]
	v_pk_mul_f32 v[0:1], v[0:1], v[156:157]
	s_nop 0
	v_cvt_pk_bf16_f32 v0, v0, v1
	v_cvt_pk_bf16_f32 v1, v2, v3
	global_store_dwordx2 v[24:25], v[0:1], off offset:3584
	v_lshl_add_u64 v[24:25], v[24:25], 0, s[4:5]
	s_cbranch_scc1 .LBB0_83
	v_writelane_b32 v255, s8, 23
	s_nop 1
	v_writelane_b32 v255, s9, 24

.LBB0_435:
	s_cmp_lt_i32 s62, 5
	s_cselect_b64 s[0:1], -1, 0
	s_cmp_gt_i32 s63, 4
	s_cselect_b64 s[2:3], -1, 0
	s_and_b64 s[0:1], s[0:1], s[2:3]
	s_andn2_b64 vcc, exec, s[0:1]
	s_cbranch_vccnz .LBB0_493
	v_readlane_b32 s0, v255, 25
	v_mov_b32_e32 v0, v212
	s_cmpk_gt_i32 s0, 0x3fff
	v_readlane_b32 s10, v255, 23
	v_readlane_b32 s1, v255, 26
	v_readlane_b32 s11, v255, 24
	s_cbranch_scc1 .LBB0_439
	v_and_b32_e32 v4, 63, v0
	v_mbcnt_lo_u32_b32 v0, -1, 0
	v_mbcnt_hi_u32_b32 v0, -1, v0
	s_waitcnt lgkmcnt(0)
	v_and_b32_e32 v1, 64, v0
	v_add_u32_e32 v1, 64, v1
	v_xor_b32_e32 v2, 1, v0
	v_cmp_lt_i32_e32 vcc, v2, v1
	v_readlane_b32 s52, v255, 7
	v_readlane_b32 s56, v255, 11
	v_cndmask_b32_e32 v2, v0, v2, vcc
	v_lshlrev_b32_e32 v26, 2, v2
	v_xor_b32_e32 v2, 2, v0
	v_cmp_lt_i32_e32 vcc, v2, v1
	v_readlane_b32 s57, v255, 12
	s_mov_b64 s[0:1], 0x2000
	v_cndmask_b32_e32 v2, v0, v2, vcc
	v_lshlrev_b32_e32 v27, 2, v2
	v_xor_b32_e32 v2, 4, v0
	v_cmp_lt_i32_e32 vcc, v2, v1
	v_readlane_b32 s53, v255, 8
	v_readlane_b32 s54, v255, 9
	v_cndmask_b32_e32 v2, v0, v2, vcc
	v_lshlrev_b32_e32 v28, 2, v2
	v_xor_b32_e32 v2, 8, v0
	v_cmp_lt_i32_e32 vcc, v2, v1
	v_readlane_b32 s55, v255, 10
	v_readlane_b32 s58, v255, 13
	v_cndmask_b32_e32 v2, v0, v2, vcc
	v_lshlrev_b32_e32 v29, 2, v2
	v_xor_b32_e32 v2, 16, v0
	v_cmp_lt_i32_e32 vcc, v2, v1
	v_readlane_b32 s59, v255, 14
	v_readlane_b32 s60, v255, 15
	v_cndmask_b32_e32 v2, v0, v2, vcc
	v_lshlrev_b32_e32 v30, 2, v2
	v_xor_b32_e32 v2, 32, v0
	v_cmp_lt_i32_e32 vcc, v2, v1
	v_mov_b32_e32 v1, 0
	v_readlane_b32 s61, v255, 16
	v_cndmask_b32_e32 v0, v0, v2, vcc
	v_lshlrev_b32_e32 v31, 2, v0
	v_lshlrev_b32_e32 v0, 4, v4
	v_lshl_add_u64 v[2:3], s[56:57], 0, v[0:1]
	v_lshl_add_u64 v[12:13], v[2:3], 0, s[0:1]
	s_mov_b64 s[0:1], 0x3000
	v_lshl_add_u64 v[14:15], v[2:3], 0, s[0:1]
	s_mov_b64 s[0:1], 0x3400
	v_lshl_add_u64 v[16:17], v[2:3], 0, s[0:1]
	s_mov_b64 s[0:1], 0x3800
	v_lshl_add_u64 v[18:19], v[2:3], 0, s[0:1]
	s_mov_b64 s[0:1], 0x3c00
	v_lshl_add_u64 v[20:21], v[2:3], 0, s[0:1]
	v_readlane_b32 s0, v255, 25
	v_readlane_b32 s1, v255, 26
	s_mov_b32 s8, s0
	s_ashr_i32 s9, s0, 31
	s_lshl_b64 s[0:1], s[8:9], 13
	s_add_u32 s0, s78, s0
	s_addc_u32 s1, s79, s1
	v_lshl_add_u64 v[2:3], s[0:1], 0, v[0:1]
	s_mov_b64 s[0:1], 0x1000
	s_ashr_i32 s11, s10, 31
	v_lshl_add_u64 v[22:23], v[2:3], 0, s[0:1]
	s_lshl_b64 s[2:3], s[10:11], 13
	s_lshl_b64 s[0:1], s[8:9], 12
	s_add_u32 s0, s80, s0
	v_lshlrev_b32_e32 v0, 3, v4
	s_addc_u32 s1, s81, s1
	v_lshl_add_u64 v[0:1], s[0:1], 0, v[0:1]
	s_mov_b64 s[0:1], 0xa200000
	v_lshl_add_u64 v[24:25], v[0:1], 0, s[0:1]
	s_mov_b32 s0, s8
	v_readlane_b32 s62, v255, 17
	v_readlane_b32 s63, v255, 18
	v_readlane_b32 s64, v255, 19
	v_readlane_b32 s65, v255, 20
	v_readlane_b32 s66, v255, 21
	v_readlane_b32 s67, v255, 22
	v_writelane_b32 v255, s0, 25
	s_lshl_b64 s[4:5], s[10:11], 12
	v_mov_b32_e32 v32, 0x358637bd
	s_mov_b32 s6, 0xf800000
	v_mov_b32_e32 v33, 0x260
	v_writelane_b32 v255, s1, 26
	s_mov_b32 s7, s8
	global_load_dwordx4 v[132:135], v[12:13], off offset:1024
	global_load_dwordx4 v[136:139], v[12:13], off offset:2048
	global_load_dwordx4 v[140:143], v[12:13], off offset:3072
	global_load_dwordx4 v[144:147], v[14:15], off
	global_load_dwordx4 v[148:151], v[16:17], off
	global_load_dwordx4 v[152:155], v[18:19], off
	global_load_dwordx4 v[156:159], v[20:21], off
.LBB0_438:
	global_load_dwordx4 v[34:37], v[22:23], off offset:-4096
	global_load_dwordx4 v[8:11], v[22:23], off offset:-3072
	global_load_dwordx4 v[38:41], v[22:23], off offset:-2048
	global_load_dwordx4 v[4:7], v[22:23], off
	global_load_dwordx4 v[42:45], v[22:23], off offset:-1024
	global_load_dwordx4 v[46:49], v[22:23], off offset:1024
	global_load_dwordx4 v[0:3], v[22:23], off offset:3072
	global_load_dwordx4 v[50:53], v[22:23], off offset:2048
	global_load_dwordx4 v[54:57], v[12:13], off
	s_add_i32 s7, s7, s10
	v_lshl_add_u64 v[22:23], v[22:23], 0, s[2:3]
	s_cmpk_lt_i32 s7, 0x4000
	s_waitcnt vmcnt(0)
	v_mov_b32_e32 v60, v35
	v_mov_b32_e32 v61, v9
	v_mov_b32_e32 v64, v37
	v_mov_b32_e32 v65, v11
	v_mov_b32_e32 v58, v34
	v_mov_b32_e32 v59, v8
	v_mov_b32_e32 v62, v36
	v_mov_b32_e32 v63, v10
	v_pk_mul_f32 v[66:67], v[40:41], v[40:41]
	v_pk_mul_f32 v[68:69], v[38:39], v[38:39]
	v_pk_mul_f32 v[60:61], v[60:61], v[60:61]
	v_pk_mul_f32 v[64:65], v[64:65], v[64:65]
	v_pk_mov_b32 v[82:83], v[68:69], v[66:67] op_sel:[1,0]
	v_mov_b32_e32 v69, v67
	v_pk_fma_f32 v[58:59], v[58:59], v[58:59], v[60:61]
	v_pk_fma_f32 v[60:61], v[62:63], v[62:63], v[64:65]
	v_mul_f32_e32 v70, v43, v43
	v_mul_f32_e32 v72, v45, v45
	v_pk_add_f32 v[62:63], v[82:83], v[68:69]
	v_pk_add_f32 v[58:59], v[58:59], v[60:61]
	v_mul_f32_e32 v81, v4, v4
	v_mul_f32_e32 v84, v5, v5
	v_mul_f32_e32 v85, v6, v6
	v_mul_f32_e32 v86, v7, v7
	v_pk_fma_f32 v[66:67], v[42:43], v[42:43], v[70:71] op_sel_hi:[1,1,0]
	v_pk_fma_f32 v[70:71], v[44:45], v[44:45], v[72:73] op_sel_hi:[1,1,0]
	v_pk_add_f32 v[60:61], v[62:63], v[62:63] op_sel:[0,1] op_sel_hi:[1,0]
	v_pk_add_f32 v[58:59], v[58:59], v[58:59] op_sel:[0,1] op_sel_hi:[1,0]
	v_pk_mul_f32 v[74:75], v[48:49], v[48:49]
	v_pk_mul_f32 v[76:77], v[46:47], v[46:47]
	v_mov_b32_e32 v67, v85
	v_mov_b32_e32 v71, v86
	v_mov_b32_e32 v61, v84
	v_mov_b32_e32 v59, v81
	v_pk_mov_b32 v[72:73], v[76:77], v[74:75] op_sel:[1,0]
	v_mov_b32_e32 v77, v75
	v_pk_add_f32 v[62:63], v[66:67], v[70:71]
	v_pk_add_f32 v[58:59], v[58:59], v[60:61]
	v_mul_f32_e32 v78, v51, v51
	v_mul_f32_e32 v80, v53, v53
	v_pk_add_f32 v[64:65], v[72:73], v[76:77]
	v_pk_add_f32 v[58:59], v[58:59], v[62:63]
	v_mul_f32_e32 v87, v0, v0
	v_mul_f32_e32 v88, v1, v1
	v_mul_f32_e32 v89, v2, v2
	v_mul_f32_e32 v90, v3, v3
	v_pk_fma_f32 v[74:75], v[50:51], v[50:51], v[78:79] op_sel_hi:[1,1,0]
	v_pk_fma_f32 v[78:79], v[52:53], v[52:53], v[80:81] op_sel_hi:[1,1,0]
	v_pk_add_f32 v[64:65], v[64:65], v[64:65] op_sel:[0,1] op_sel_hi:[1,0]
	v_pk_add_f32 v[58:59], v[58:59], v[58:59] op_sel:[0,1] op_sel_hi:[1,0]
	v_mov_b32_e32 v75, v89
	v_mov_b32_e32 v79, v90
	v_mov_b32_e32 v65, v88
	v_mov_b32_e32 v59, v87
	v_pk_add_f32 v[66:67], v[74:75], v[78:79]
	v_pk_add_f32 v[58:59], v[58:59], v[64:65]
	s_nop 0
	v_pk_add_f32 v[58:59], v[58:59], v[66:67]
	s_nop 0
	v_add_f32_e32 v58, v58, v59
	ds_bpermute_b32 v59, v26, v58
	s_waitcnt lgkmcnt(0)
	v_add_f32_e32 v58, v58, v59
	ds_bpermute_b32 v59, v27, v58
	s_waitcnt lgkmcnt(0)
	v_add_f32_e32 v58, v58, v59
	ds_bpermute_b32 v59, v28, v58
	s_waitcnt lgkmcnt(0)
	v_add_f32_e32 v58, v58, v59
	ds_bpermute_b32 v59, v29, v58
	s_waitcnt lgkmcnt(0)
	v_add_f32_e32 v58, v58, v59
	ds_bpermute_b32 v59, v30, v58
	s_waitcnt lgkmcnt(0)
	v_add_f32_e32 v58, v58, v59
	ds_bpermute_b32 v59, v31, v58
	s_waitcnt lgkmcnt(0)
	v_add_f32_e32 v58, v58, v59
	v_fmamk_f32 v58, v58, 0x3a000000, v32
	v_mul_f32_e32 v59, 0x4f800000, v58
	v_cmp_gt_f32_e32 vcc, s6, v58
	s_nop 1
	v_cndmask_b32_e32 v58, v58, v59, vcc
	v_sqrt_f32_e32 v59, v58
	s_nop 0
	v_add_u32_e32 v60, -1, v59
	v_add_u32_e32 v61, 1, v59
	v_fma_f32 v62, -v60, v59, v58
	v_fma_f32 v63, -v61, v59, v58
	v_cmp_ge_f32_e64 s[0:1], 0, v62
	s_nop 1
	v_cndmask_b32_e64 v59, v59, v60, s[0:1]
	v_cmp_lt_f32_e64 s[0:1], 0, v63
	s_nop 1
	v_cndmask_b32_e64 v59, v59, v61, s[0:1]
	v_mul_f32_e32 v60, 0x37800000, v59
	v_cndmask_b32_e32 v59, v59, v60, vcc
	v_cmp_class_f32_e32 vcc, v58, v33
	s_nop 1
	v_cndmask_b32_e32 v58, v59, v58, vcc
	v_div_scale_f32 v59, s[0:1], v58, v58, 1.0
	v_rcp_f32_e32 v61, v59
	v_div_scale_f32 v60, vcc, 1.0, v58, 1.0
	v_fma_f32 v62, -v59, v61, 1.0
	v_fmac_f32_e32 v61, v62, v61
	v_mul_f32_e32 v62, v60, v61
	v_fma_f32 v63, -v59, v62, v60
	v_fmac_f32_e32 v62, v63, v61
	v_fma_f32 v59, -v59, v62, v60
	v_div_fmas_f32 v59, v59, v61, v62
	v_div_fixup_f32 v58, v59, v58, 1.0
	v_pk_mul_f32 v[34:35], v[34:35], v[58:59] op_sel_hi:[1,0]
	v_pk_mul_f32 v[36:37], v[36:37], v[58:59] op_sel_hi:[1,0]
	v_pk_mul_f32 v[34:35], v[54:55], v[34:35]
	v_pk_mul_f32 v[36:37], v[56:57], v[36:37]
	v_cvt_pk_bf16_f32 v34, v34, v35
	v_cvt_pk_bf16_f32 v35, v36, v37
	global_store_dwordx2 v[24:25], v[34:35], off
	v_pk_mul_f32 v[8:9], v[8:9], v[58:59] op_sel_hi:[1,0]
	v_pk_mul_f32 v[10:11], v[10:11], v[58:59] op_sel_hi:[1,0]
	v_pk_mul_f32 v[4:5], v[4:5], v[58:59] op_sel_hi:[1,0]
	v_pk_mul_f32 v[6:7], v[6:7], v[58:59] op_sel_hi:[1,0]
	v_pk_mul_f32 v[0:1], v[0:1], v[58:59] op_sel_hi:[1,0]
	v_pk_mul_f32 v[2:3], v[2:3], v[58:59] op_sel_hi:[1,0]
	v_pk_mul_f32 v[10:11], v[134:135], v[10:11]
	v_pk_mul_f32 v[8:9], v[132:133], v[8:9]
	v_pk_mul_f32 v[34:35], v[38:39], v[58:59] op_sel_hi:[1,0]
	v_cvt_pk_bf16_f32 v8, v8, v9
	v_cvt_pk_bf16_f32 v9, v10, v11
	global_store_dwordx2 v[24:25], v[8:9], off offset:512
	v_pk_mul_f32 v[36:37], v[40:41], v[58:59] op_sel_hi:[1,0]
	v_pk_mul_f32 v[8:9], v[136:137], v[34:35]
	v_pk_mul_f32 v[10:11], v[138:139], v[36:37]
	v_cvt_pk_bf16_f32 v8, v8, v9
	v_cvt_pk_bf16_f32 v9, v10, v11
	global_store_dwordx2 v[24:25], v[8:9], off offset:1024
	v_pk_mul_f32 v[34:35], v[42:43], v[58:59] op_sel_hi:[1,0]
	v_pk_mul_f32 v[36:37], v[44:45], v[58:59] op_sel_hi:[1,0]
	v_pk_mul_f32 v[8:9], v[140:141], v[34:35]
	v_pk_mul_f32 v[10:11], v[142:143], v[36:37]
	v_cvt_pk_bf16_f32 v8, v8, v9
	v_cvt_pk_bf16_f32 v9, v10, v11
	global_store_dwordx2 v[24:25], v[8:9], off offset:1536
	v_pk_mul_f32 v[6:7], v[146:147], v[6:7]
	v_pk_mul_f32 v[4:5], v[144:145], v[4:5]
	v_pk_mul_f32 v[8:9], v[46:47], v[58:59] op_sel_hi:[1,0]
	v_cvt_pk_bf16_f32 v4, v4, v5
	v_cvt_pk_bf16_f32 v5, v6, v7
	global_store_dwordx2 v[24:25], v[4:5], off offset:2048
	v_pk_mul_f32 v[10:11], v[48:49], v[58:59] op_sel_hi:[1,0]
	v_pk_mul_f32 v[4:5], v[148:149], v[8:9]
	v_pk_mul_f32 v[6:7], v[150:151], v[10:11]
	v_cvt_pk_bf16_f32 v4, v4, v5
	v_cvt_pk_bf16_f32 v5, v6, v7
	global_store_dwordx2 v[24:25], v[4:5], off offset:2560
	v_pk_mul_f32 v[8:9], v[50:51], v[58:59] op_sel_hi:[1,0]
	v_pk_mul_f32 v[10:11], v[52:53], v[58:59] op_sel_hi:[1,0]
	v_pk_mul_f32 v[4:5], v[8:9], v[152:153]
	v_pk_mul_f32 v[6:7], v[10:11], v[154:155]
	v_cvt_pk_bf16_f32 v4, v4, v5
	v_cvt_pk_bf16_f32 v5, v6, v7
	global_store_dwordx2 v[24:25], v[4:5], off offset:3072
	v_pk_mul_f32 v[2:3], v[2:3], v[158:159]
	v_pk_mul_f32 v[0:1], v[0:1], v[156:157]
	s_nop 0
	v_cvt_pk_bf16_f32 v0, v0, v1
	v_cvt_pk_bf16_f32 v1, v2, v3
	global_store_dwordx2 v[24:25], v[0:1], off offset:3584
	v_lshl_add_u64 v[24:25], v[24:25], 0, s[4:5]
	s_cbranch_scc1 .LBB0_438

.LBB0_1191:
	s_nop 1
	v_add_u32_e32 v64, s44, v167
	v_ashrrev_i32_e32 v65, 31, v64
	v_lshlrev_b64 v[68:69], 8, v[64:65]
	v_lshl_add_u64 v[64:65], v[116:117], 0, v[68:69]
	global_load_dwordx4 v[80:83], v[64:65], off
	v_lshl_add_u64 v[64:65], v[118:119], 0, v[68:69]
	global_load_dwordx4 v[84:87], v[64:65], off
	v_add_u32_e32 v64, s44, v168
	v_ashrrev_i32_e32 v65, 31, v64
	v_lshlrev_b64 v[68:69], 8, v[64:65]
	v_lshl_add_u64 v[64:65], v[116:117], 0, v[68:69]
	global_load_dwordx4 v[88:91], v[64:65], off
	v_lshl_add_u64 v[64:65], v[118:119], 0, v[68:69]
	global_load_dwordx4 v[92:95], v[64:65], off
	v_or_b32_e32 v112, s44, v132
	v_lshlrev_b32_e32 v78, 2, v132
	v_lshlrev_b64 v[68:69], 2, v[112:113]
	v_lshl_add_u64 v[70:71], s[66:67], 0, v[68:69]
	v_lshl_add_u64 v[68:69], s[68:69], 0, v[68:69]
	global_load_dword v231, v[68:69], off
	global_load_dword v230, v[70:71], off
	v_lshlrev_b64 v[64:65], 9, v[112:113]
	v_lshl_add_u64 v[64:65], v[120:121], 0, v[64:65]
	global_load_dwordx4 v[96:99], v[64:65], off
	v_or_b32_e32 v112, s44, v170
	v_lshlrev_b64 v[64:65], 9, v[112:113]
	v_lshl_add_u64 v[64:65], v[120:121], 0, v[64:65]
	global_load_dwordx4 v[100:103], v[64:65], off
	global_load_dword v232, v78, s[74:75] offset:64
	v_add_u32_e32 v112, s44, v132
	v_lshl_add_u64 v[68:69], v[112:113], 2, s[68:69]
	global_load_dword v233, v[68:69], off offset:64
	v_or_b32_e32 v112, s44, v172
	v_lshlrev_b64 v[64:65], 9, v[112:113]
	v_lshl_add_u64 v[64:65], v[120:121], 0, v[64:65]
	global_load_dwordx4 v[104:107], v[64:65], off
	global_load_dword v234, v78, s[74:75] offset:128
	global_load_dword v235, v[68:69], off offset:128
	v_or_b32_e32 v112, s44, v174
	v_lshlrev_b64 v[64:65], 9, v[112:113]
	v_lshl_add_u64 v[64:65], v[120:121], 0, v[64:65]
	global_load_dwordx4 v[108:111], v[64:65], off
	global_load_dword v236, v78, s[74:75] offset:192
	global_load_dword v237, v[68:69], off offset:192
	s_and_saveexec_b64 s[92:93], s[2:3]
	s_cbranch_execz .Lmy_ml_nol
	v_add_u32_e32 v64, s44, v114
	v_ashrrev_i32_e32 v65, 31, v64
	v_lshl_add_u64 v[66:67], v[114:115], 2, s[74:75]
	v_lshlrev_b64 v[64:65], 2, v[64:65]
	global_load_dword v238, v[66:67], off
	v_lshl_add_u64 v[66:67], s[68:69], 0, v[64:65]
	global_load_dword v239, v[66:67], off
	v_lshl_add_u64 v[64:65], s[64:65], 0, v[64:65]
	global_load_dword v240, v[64:65], off
.Lmy_ml_nol:
	s_or_b64 exec, exec, s[92:93]
	s_waitcnt vmcnt(0)
	ds_write_b128 v218, v[80:83]
	ds_write_b128 v218, v[84:87] offset:16384
	ds_write_b128 v219, v[88:91]
	ds_write_b128 v219, v[92:95] offset:16384
	v_and_b32_e32 v69, 0xffff0000, v96
	v_and_b32_e32 v71, 0xffff0000, v97
	v_sub_f32_e32 v70, v229, v230
	v_add_f32_e32 v68, v70, v231
	v_sub_f32_e32 v68, v68, v135
	v_mul_f32_e32 v68, 0x3fb8aa3b, v68
	v_exp_f32_e32 v72, v68
	v_lshlrev_b32_e32 v68, 16, v96
	v_lshlrev_b32_e32 v70, 16, v97
	v_lshlrev_b32_e32 v74, 16, v99
	v_pk_mul_f32 v[68:69], v[72:73], v[68:69] op_sel_hi:[0,1]
	v_pk_mul_f32 v[70:71], v[72:73], v[70:71] op_sel_hi:[0,1]
	v_cvt_pk_bf16_f32 v68, v68, v69
	v_cvt_pk_bf16_f32 v69, v70, v71
	v_lshlrev_b32_e32 v70, 16, v98
	v_and_b32_e32 v71, 0xffff0000, v98
	v_and_b32_e32 v75, 0xffff0000, v99
	v_pk_mul_f32 v[70:71], v[72:73], v[70:71] op_sel_hi:[0,1]
	v_pk_mul_f32 v[72:73], v[72:73], v[74:75] op_sel_hi:[0,1]
	v_cvt_pk_bf16_f32 v70, v70, v71
	v_cvt_pk_bf16_f32 v71, v72, v73
	v_add_u32_e32 v72, 0, v169
	ds_write_b128 v72, v[96:99] offset:32768
	v_add_u32_e32 v64, s60, v169
	ds_write_b128 v64, v[68:71]
	v_and_b32_e32 v69, 0xffff0000, v100
	v_and_b32_e32 v71, 0xffff0000, v101
	v_sub_f32_e32 v70, v229, v232
	v_add_f32_e32 v68, v70, v233
	v_sub_f32_e32 v68, v68, v135
	v_mul_f32_e32 v68, 0x3fb8aa3b, v68
	v_exp_f32_e32 v72, v68
	v_lshlrev_b32_e32 v68, 16, v100
	v_lshlrev_b32_e32 v70, 16, v101
	v_lshlrev_b32_e32 v74, 16, v103
	v_pk_mul_f32 v[68:69], v[72:73], v[68:69] op_sel_hi:[0,1]
	v_pk_mul_f32 v[70:71], v[72:73], v[70:71] op_sel_hi:[0,1]
	v_cvt_pk_bf16_f32 v68, v68, v69
	v_cvt_pk_bf16_f32 v69, v70, v71
	v_lshlrev_b32_e32 v70, 16, v102
	v_and_b32_e32 v71, 0xffff0000, v102
	v_and_b32_e32 v75, 0xffff0000, v103
	v_pk_mul_f32 v[70:71], v[72:73], v[70:71] op_sel_hi:[0,1]
	v_pk_mul_f32 v[72:73], v[72:73], v[74:75] op_sel_hi:[0,1]
	v_cvt_pk_bf16_f32 v70, v70, v71
	v_cvt_pk_bf16_f32 v71, v72, v73
	v_add_u32_e32 v72, 0, v171
	ds_write_b128 v72, v[100:103] offset:32768
	v_add_u32_e32 v64, s60, v171
	ds_write_b128 v64, v[68:71]
	v_and_b32_e32 v69, 0xffff0000, v104
	v_and_b32_e32 v71, 0xffff0000, v105
	v_sub_f32_e32 v70, v229, v234
	v_add_f32_e32 v68, v70, v235
	v_sub_f32_e32 v68, v68, v135
	v_mul_f32_e32 v68, 0x3fb8aa3b, v68
	v_exp_f32_e32 v72, v68
	v_lshlrev_b32_e32 v68, 16, v104
	v_lshlrev_b32_e32 v70, 16, v105
	v_lshlrev_b32_e32 v74, 16, v107
	v_pk_mul_f32 v[68:69], v[72:73], v[68:69] op_sel_hi:[0,1]
	v_pk_mul_f32 v[70:71], v[72:73], v[70:71] op_sel_hi:[0,1]
	v_cvt_pk_bf16_f32 v68, v68, v69
	v_cvt_pk_bf16_f32 v69, v70, v71
	v_lshlrev_b32_e32 v70, 16, v106
	v_and_b32_e32 v71, 0xffff0000, v106
	v_and_b32_e32 v75, 0xffff0000, v107
	v_pk_mul_f32 v[70:71], v[72:73], v[70:71] op_sel_hi:[0,1]
	v_pk_mul_f32 v[72:73], v[72:73], v[74:75] op_sel_hi:[0,1]
	v_cvt_pk_bf16_f32 v70, v70, v71
	v_cvt_pk_bf16_f32 v71, v72, v73
	v_add_u32_e32 v72, 0, v173
	ds_write_b128 v72, v[104:107] offset:32768
	v_add_u32_e32 v64, s60, v173
	ds_write_b128 v64, v[68:71]
	v_and_b32_e32 v69, 0xffff0000, v108
	v_and_b32_e32 v71, 0xffff0000, v109
	v_sub_f32_e32 v70, v229, v236
	v_add_f32_e32 v68, v70, v237
	v_sub_f32_e32 v68, v68, v135
	v_mul_f32_e32 v68, 0x3fb8aa3b, v68
	v_exp_f32_e32 v72, v68
	v_lshlrev_b32_e32 v68, 16, v108
	v_lshlrev_b32_e32 v70, 16, v109
	v_lshlrev_b32_e32 v74, 16, v111
	v_pk_mul_f32 v[68:69], v[72:73], v[68:69] op_sel_hi:[0,1]
	v_pk_mul_f32 v[70:71], v[72:73], v[70:71] op_sel_hi:[0,1]
	v_cvt_pk_bf16_f32 v68, v68, v69
	v_cvt_pk_bf16_f32 v69, v70, v71
	v_lshlrev_b32_e32 v70, 16, v110
	v_and_b32_e32 v71, 0xffff0000, v110
	v_and_b32_e32 v75, 0xffff0000, v111
	v_pk_mul_f32 v[70:71], v[72:73], v[70:71] op_sel_hi:[0,1]
	v_pk_mul_f32 v[72:73], v[72:73], v[74:75] op_sel_hi:[0,1]
	v_cvt_pk_bf16_f32 v70, v70, v71
	v_cvt_pk_bf16_f32 v71, v72, v73
	v_add_u32_e32 v72, 0, v175
	ds_write_b128 v72, v[108:111] offset:32768
	v_add_u32_e32 v64, s60, v175
	ds_write_b128 v64, v[68:71]
	s_and_saveexec_b64 s[92:93], s[2:3]
	s_cbranch_execz .LBB0_1193
	ds_write_b32 v155, v238
	ds_write_b32 v156, v239
	v_max_f32_e32 v65, v134, v134
	v_max_f32_e32 v64, v240, v240
	v_max_f32_e32 v64, v65, v64
	v_add_f32_e32 v64, v238, v64
	ds_write_b32 v157, v64
	v_sub_f32_e32 v64, v229, v238
	v_add_f32_e32 v64, v64, v239
	v_sub_f32_e32 v64, v64, v135
	v_mul_f32_e32 v64, 0x3fb8aa3b, v64
	v_exp_f32_e32 v64, v64
	s_nop 0
	ds_write_b32 v158, v64

.LBB0_1405:
	s_cmp_lt_i32 s62, 16
	s_cselect_b64 s[0:1], -1, 0
	s_cmp_gt_i32 s63, 15
	s_cselect_b64 s[2:3], -1, 0
	s_and_b64 s[0:1], s[0:1], s[2:3]
	s_andn2_b64 vcc, exec, s[0:1]
	s_cbranch_vccnz .LBB0_1463
	v_readlane_b32 s0, v255, 25
	v_mov_b32_e32 v0, v212
	s_cmpk_gt_i32 s0, 0x3fff
	v_readlane_b32 s1, v255, 26
	s_cbranch_scc1 .LBB0_1409
	v_and_b32_e32 v4, 63, v0
	v_mbcnt_lo_u32_b32 v0, -1, 0
	v_mbcnt_hi_u32_b32 v0, -1, v0
	v_and_b32_e32 v1, 64, v0
	v_add_u32_e32 v1, 64, v1
	v_xor_b32_e32 v2, 1, v0
	v_cmp_lt_i32_e32 vcc, v2, v1
	v_readlane_b32 s0, v255, 7
	v_readlane_b32 s1, v255, 8
	v_cndmask_b32_e32 v2, v0, v2, vcc
	v_lshlrev_b32_e32 v26, 2, v2
	v_xor_b32_e32 v2, 2, v0
	v_cmp_lt_i32_e32 vcc, v2, v1
	v_readlane_b32 s4, v255, 11
	v_readlane_b32 s5, v255, 12
	v_cndmask_b32_e32 v2, v0, v2, vcc
	v_lshlrev_b32_e32 v27, 2, v2
	v_xor_b32_e32 v2, 4, v0
	v_cmp_lt_i32_e32 vcc, v2, v1
	s_mov_b64 s[0:1], 0x6000
	v_readlane_b32 s8, v255, 15
	v_cndmask_b32_e32 v2, v0, v2, vcc
	v_lshlrev_b32_e32 v28, 2, v2
	v_xor_b32_e32 v2, 8, v0
	v_cmp_lt_i32_e32 vcc, v2, v1
	v_readlane_b32 s9, v255, 16
	v_readlane_b32 s2, v255, 9
	v_cndmask_b32_e32 v2, v0, v2, vcc
	v_lshlrev_b32_e32 v29, 2, v2
	v_xor_b32_e32 v2, 16, v0
	v_cmp_lt_i32_e32 vcc, v2, v1
	v_readlane_b32 s3, v255, 10
	v_readlane_b32 s6, v255, 13
	v_cndmask_b32_e32 v2, v0, v2, vcc
	v_lshlrev_b32_e32 v30, 2, v2
	v_xor_b32_e32 v2, 32, v0
	v_cmp_lt_i32_e32 vcc, v2, v1
	v_mov_b32_e32 v1, 0
	v_readlane_b32 s7, v255, 14
	v_cndmask_b32_e32 v0, v0, v2, vcc
	v_lshlrev_b32_e32 v31, 2, v0
	v_lshlrev_b32_e32 v0, 4, v4
	v_lshl_add_u64 v[2:3], s[4:5], 0, v[0:1]
	v_lshl_add_u64 v[12:13], v[2:3], 0, s[0:1]
	s_mov_b64 s[0:1], 0x7000
	v_lshl_add_u64 v[14:15], v[2:3], 0, s[0:1]
	s_mov_b64 s[0:1], 0x7400
	v_lshl_add_u64 v[16:17], v[2:3], 0, s[0:1]
	s_mov_b64 s[0:1], 0x7800
	v_lshl_add_u64 v[18:19], v[2:3], 0, s[0:1]
	s_mov_b64 s[0:1], 0x7c00
	v_lshl_add_u64 v[20:21], v[2:3], 0, s[0:1]
	v_readlane_b32 s0, v255, 25
	v_readlane_b32 s1, v255, 26
	s_mov_b32 s8, s0
	s_ashr_i32 s9, s0, 31
	s_lshl_b64 s[0:1], s[8:9], 13
	s_add_u32 s0, s78, s0
	s_addc_u32 s1, s79, s1
	v_lshl_add_u64 v[2:3], s[0:1], 0, v[0:1]
	s_mov_b64 s[0:1], 0x1000
	s_ashr_i32 s75, s74, 31
	v_lshl_add_u64 v[22:23], v[2:3], 0, s[0:1]
	s_lshl_b64 s[2:3], s[74:75], 13
	s_lshl_b64 s[0:1], s[8:9], 12
	s_add_u32 s0, s80, s0
	v_lshlrev_b32_e32 v0, 3, v4
	s_addc_u32 s1, s81, s1
	v_lshl_add_u64 v[0:1], s[0:1], 0, v[0:1]
	s_mov_b64 s[0:1], 0xa200000
	v_lshl_add_u64 v[24:25], v[0:1], 0, s[0:1]
	s_mov_b32 s0, s8
	v_readlane_b32 s10, v255, 17
	v_readlane_b32 s11, v255, 18
	v_readlane_b32 s12, v255, 19
	v_readlane_b32 s13, v255, 20
	v_readlane_b32 s14, v255, 21
	v_readlane_b32 s15, v255, 22
	v_writelane_b32 v255, s0, 25
	s_lshl_b64 s[4:5], s[74:75], 12
	v_mov_b32_e32 v32, 0x358637bd
	s_mov_b32 s6, 0xf800000
	v_mov_b32_e32 v33, 0x260
	v_writelane_b32 v255, s1, 26
	s_mov_b32 s7, s8
	global_load_dwordx4 v[132:135], v[12:13], off offset:1024
	global_load_dwordx4 v[136:139], v[12:13], off offset:2048
	global_load_dwordx4 v[140:143], v[12:13], off offset:3072
	global_load_dwordx4 v[144:147], v[14:15], off
	global_load_dwordx4 v[148:151], v[16:17], off
	global_load_dwordx4 v[152:155], v[18:19], off
	global_load_dwordx4 v[156:159], v[20:21], off
.LBB0_1408:
	global_load_dwordx4 v[34:37], v[22:23], off offset:-4096
	global_load_dwordx4 v[8:11], v[22:23], off offset:-3072
	global_load_dwordx4 v[38:41], v[22:23], off offset:-2048
	global_load_dwordx4 v[4:7], v[22:23], off
	global_load_dwordx4 v[42:45], v[22:23], off offset:-1024
	global_load_dwordx4 v[46:49], v[22:23], off offset:1024
	global_load_dwordx4 v[0:3], v[22:23], off offset:3072
	global_load_dwordx4 v[50:53], v[22:23], off offset:2048
	global_load_dwordx4 v[54:57], v[12:13], off
	s_add_i32 s7, s7, s74
	v_lshl_add_u64 v[22:23], v[22:23], 0, s[2:3]
	s_cmpk_lt_i32 s7, 0x4000
	s_waitcnt vmcnt(0)
	v_mov_b32_e32 v60, v35
	v_mov_b32_e32 v61, v9
	v_mov_b32_e32 v64, v37
	v_mov_b32_e32 v65, v11
	v_mov_b32_e32 v58, v34
	v_mov_b32_e32 v59, v8
	v_mov_b32_e32 v62, v36
	v_mov_b32_e32 v63, v10
	v_pk_mul_f32 v[66:67], v[40:41], v[40:41]
	v_pk_mul_f32 v[68:69], v[38:39], v[38:39]
	v_pk_mul_f32 v[60:61], v[60:61], v[60:61]
	v_pk_mul_f32 v[64:65], v[64:65], v[64:65]
	v_pk_mov_b32 v[82:83], v[68:69], v[66:67] op_sel:[1,0]
	v_mov_b32_e32 v69, v67
	v_pk_fma_f32 v[58:59], v[58:59], v[58:59], v[60:61]
	v_pk_fma_f32 v[60:61], v[62:63], v[62:63], v[64:65]
	v_mul_f32_e32 v70, v43, v43
	v_mul_f32_e32 v72, v45, v45
	v_pk_add_f32 v[62:63], v[82:83], v[68:69]
	v_pk_add_f32 v[58:59], v[58:59], v[60:61]
	v_mul_f32_e32 v81, v4, v4
	v_mul_f32_e32 v84, v5, v5
	v_mul_f32_e32 v85, v6, v6
	v_mul_f32_e32 v86, v7, v7
	v_pk_fma_f32 v[66:67], v[42:43], v[42:43], v[70:71] op_sel_hi:[1,1,0]
	v_pk_fma_f32 v[70:71], v[44:45], v[44:45], v[72:73] op_sel_hi:[1,1,0]
	v_pk_add_f32 v[60:61], v[62:63], v[62:63] op_sel:[0,1] op_sel_hi:[1,0]
	v_pk_add_f32 v[58:59], v[58:59], v[58:59] op_sel:[0,1] op_sel_hi:[1,0]
	v_pk_mul_f32 v[74:75], v[48:49], v[48:49]
	v_pk_mul_f32 v[76:77], v[46:47], v[46:47]
	v_mov_b32_e32 v67, v85
	v_mov_b32_e32 v71, v86
	v_mov_b32_e32 v61, v84
	v_mov_b32_e32 v59, v81
	v_pk_mov_b32 v[72:73], v[76:77], v[74:75] op_sel:[1,0]
	v_mov_b32_e32 v77, v75
	v_pk_add_f32 v[62:63], v[66:67], v[70:71]
	v_pk_add_f32 v[58:59], v[58:59], v[60:61]
	v_mul_f32_e32 v78, v51, v51
	v_mul_f32_e32 v80, v53, v53
	v_pk_add_f32 v[64:65], v[72:73], v[76:77]
	v_pk_add_f32 v[58:59], v[58:59], v[62:63]
	v_mul_f32_e32 v87, v0, v0
	v_mul_f32_e32 v88, v1, v1
	v_mul_f32_e32 v89, v2, v2
	v_mul_f32_e32 v90, v3, v3
	v_pk_fma_f32 v[74:75], v[50:51], v[50:51], v[78:79] op_sel_hi:[1,1,0]
	v_pk_fma_f32 v[78:79], v[52:53], v[52:53], v[80:81] op_sel_hi:[1,1,0]
	v_pk_add_f32 v[64:65], v[64:65], v[64:65] op_sel:[0,1] op_sel_hi:[1,0]
	v_pk_add_f32 v[58:59], v[58:59], v[58:59] op_sel:[0,1] op_sel_hi:[1,0]
	v_mov_b32_e32 v75, v89
	v_mov_b32_e32 v79, v90
	v_mov_b32_e32 v65, v88
	v_mov_b32_e32 v59, v87
	v_pk_add_f32 v[66:67], v[74:75], v[78:79]
	v_pk_add_f32 v[58:59], v[58:59], v[64:65]
	s_nop 0
	v_pk_add_f32 v[58:59], v[58:59], v[66:67]
	s_nop 0
	v_add_f32_e32 v58, v58, v59
	ds_bpermute_b32 v59, v26, v58
	s_waitcnt lgkmcnt(0)
	v_add_f32_e32 v58, v58, v59
	ds_bpermute_b32 v59, v27, v58
	s_waitcnt lgkmcnt(0)
	v_add_f32_e32 v58, v58, v59
	ds_bpermute_b32 v59, v28, v58
	s_waitcnt lgkmcnt(0)
	v_add_f32_e32 v58, v58, v59
	ds_bpermute_b32 v59, v29, v58
	s_waitcnt lgkmcnt(0)
	v_add_f32_e32 v58, v58, v59
	ds_bpermute_b32 v59, v30, v58
	s_waitcnt lgkmcnt(0)
	v_add_f32_e32 v58, v58, v59
	ds_bpermute_b32 v59, v31, v58
	s_waitcnt lgkmcnt(0)
	v_add_f32_e32 v58, v58, v59
	v_fmamk_f32 v58, v58, 0x3a000000, v32
	v_mul_f32_e32 v59, 0x4f800000, v58
	v_cmp_gt_f32_e32 vcc, s6, v58
	s_nop 1
	v_cndmask_b32_e32 v58, v58, v59, vcc
	v_sqrt_f32_e32 v59, v58
	s_nop 0
	v_add_u32_e32 v60, -1, v59
	v_add_u32_e32 v61, 1, v59
	v_fma_f32 v62, -v60, v59, v58
	v_fma_f32 v63, -v61, v59, v58
	v_cmp_ge_f32_e64 s[0:1], 0, v62
	s_nop 1
	v_cndmask_b32_e64 v59, v59, v60, s[0:1]
	v_cmp_lt_f32_e64 s[0:1], 0, v63
	s_nop 1
	v_cndmask_b32_e64 v59, v59, v61, s[0:1]
	v_mul_f32_e32 v60, 0x37800000, v59
	v_cndmask_b32_e32 v59, v59, v60, vcc
	v_cmp_class_f32_e32 vcc, v58, v33
	s_nop 1
	v_cndmask_b32_e32 v58, v59, v58, vcc
	v_div_scale_f32 v59, s[0:1], v58, v58, 1.0
	v_rcp_f32_e32 v61, v59
	v_div_scale_f32 v60, vcc, 1.0, v58, 1.0
	v_fma_f32 v62, -v59, v61, 1.0
	v_fmac_f32_e32 v61, v62, v61
	v_mul_f32_e32 v62, v60, v61
	v_fma_f32 v63, -v59, v62, v60
	v_fmac_f32_e32 v62, v63, v61
	v_fma_f32 v59, -v59, v62, v60
	v_div_fmas_f32 v59, v59, v61, v62
	v_div_fixup_f32 v58, v59, v58, 1.0
	v_pk_mul_f32 v[34:35], v[34:35], v[58:59] op_sel_hi:[1,0]
	v_pk_mul_f32 v[36:37], v[36:37], v[58:59] op_sel_hi:[1,0]
	v_pk_mul_f32 v[34:35], v[54:55], v[34:35]
	v_pk_mul_f32 v[36:37], v[56:57], v[36:37]
	v_cvt_pk_bf16_f32 v34, v34, v35
	v_cvt_pk_bf16_f32 v35, v36, v37
	global_store_dwordx2 v[24:25], v[34:35], off
	v_pk_mul_f32 v[8:9], v[8:9], v[58:59] op_sel_hi:[1,0]
	v_pk_mul_f32 v[10:11], v[10:11], v[58:59] op_sel_hi:[1,0]
	v_pk_mul_f32 v[4:5], v[4:5], v[58:59] op_sel_hi:[1,0]
	v_pk_mul_f32 v[6:7], v[6:7], v[58:59] op_sel_hi:[1,0]
	v_pk_mul_f32 v[0:1], v[0:1], v[58:59] op_sel_hi:[1,0]
	v_pk_mul_f32 v[2:3], v[2:3], v[58:59] op_sel_hi:[1,0]
	v_pk_mul_f32 v[10:11], v[134:135], v[10:11]
	v_pk_mul_f32 v[8:9], v[132:133], v[8:9]
	v_pk_mul_f32 v[34:35], v[38:39], v[58:59] op_sel_hi:[1,0]
	v_cvt_pk_bf16_f32 v8, v8, v9
	v_cvt_pk_bf16_f32 v9, v10, v11
	global_store_dwordx2 v[24:25], v[8:9], off offset:512
	v_pk_mul_f32 v[36:37], v[40:41], v[58:59] op_sel_hi:[1,0]
	v_pk_mul_f32 v[8:9], v[136:137], v[34:35]
	v_pk_mul_f32 v[10:11], v[138:139], v[36:37]
	v_cvt_pk_bf16_f32 v8, v8, v9
	v_cvt_pk_bf16_f32 v9, v10, v11
	global_store_dwordx2 v[24:25], v[8:9], off offset:1024
	v_pk_mul_f32 v[34:35], v[42:43], v[58:59] op_sel_hi:[1,0]
	v_pk_mul_f32 v[36:37], v[44:45], v[58:59] op_sel_hi:[1,0]
	v_pk_mul_f32 v[8:9], v[140:141], v[34:35]
	v_pk_mul_f32 v[10:11], v[142:143], v[36:37]
	v_cvt_pk_bf16_f32 v8, v8, v9
	v_cvt_pk_bf16_f32 v9, v10, v11
	global_store_dwordx2 v[24:25], v[8:9], off offset:1536
	v_pk_mul_f32 v[6:7], v[146:147], v[6:7]
	v_pk_mul_f32 v[4:5], v[144:145], v[4:5]
	v_pk_mul_f32 v[8:9], v[46:47], v[58:59] op_sel_hi:[1,0]
	v_cvt_pk_bf16_f32 v4, v4, v5
	v_cvt_pk_bf16_f32 v5, v6, v7
	global_store_dwordx2 v[24:25], v[4:5], off offset:2048
	v_pk_mul_f32 v[10:11], v[48:49], v[58:59] op_sel_hi:[1,0]
	v_pk_mul_f32 v[4:5], v[148:149], v[8:9]
	v_pk_mul_f32 v[6:7], v[150:151], v[10:11]
	v_cvt_pk_bf16_f32 v4, v4, v5
	v_cvt_pk_bf16_f32 v5, v6, v7
	global_store_dwordx2 v[24:25], v[4:5], off offset:2560
	v_pk_mul_f32 v[8:9], v[50:51], v[58:59] op_sel_hi:[1,0]
	v_pk_mul_f32 v[10:11], v[52:53], v[58:59] op_sel_hi:[1,0]
	v_pk_mul_f32 v[4:5], v[8:9], v[152:153]
	v_pk_mul_f32 v[6:7], v[10:11], v[154:155]
	v_cvt_pk_bf16_f32 v4, v4, v5
	v_cvt_pk_bf16_f32 v5, v6, v7
	global_store_dwordx2 v[24:25], v[4:5], off offset:3072
	v_pk_mul_f32 v[2:3], v[2:3], v[158:159]
	v_pk_mul_f32 v[0:1], v[0:1], v[156:157]
	s_nop 0
	v_cvt_pk_bf16_f32 v0, v0, v1
	v_cvt_pk_bf16_f32 v1, v2, v3
	global_store_dwordx2 v[24:25], v[0:1], off offset:3584
	v_lshl_add_u64 v[24:25], v[24:25], 0, s[4:5]
	s_cbranch_scc1 .LBB0_1408

.LBB0_1759:
	s_cmp_lt_i32 s62, 20
	s_cselect_b64 s[0:1], -1, 0
	s_cmp_gt_i32 s63, 19
	s_cselect_b64 s[2:3], -1, 0
	s_and_b64 s[0:1], s[0:1], s[2:3]
	s_andn2_b64 vcc, exec, s[0:1]
	s_cbranch_vccnz .LBB0_1817
	v_readlane_b32 s6, v255, 25
	s_cmpk_gt_i32 s6, 0x3fff
	v_readlane_b32 s7, v255, 26
	s_cbranch_scc1 .LBB0_1763
	s_waitcnt lgkmcnt(0)
	v_mbcnt_lo_u32_b32 v1, -1, 0
	v_mbcnt_hi_u32_b32 v1, -1, v1
	v_and_b32_e32 v2, 64, v1
	v_add_u32_e32 v2, 64, v2
	v_xor_b32_e32 v3, 1, v1
	v_cmp_lt_i32_e32 vcc, v3, v2
	v_and_b32_e32 v0, 63, v212
	v_readlane_b32 s8, v255, 7
	v_cndmask_b32_e32 v3, v1, v3, vcc
	v_lshlrev_b32_e32 v24, 2, v3
	v_xor_b32_e32 v3, 2, v1
	v_cmp_lt_i32_e32 vcc, v3, v2
	v_lshlrev_b32_e32 v0, 4, v0
	v_readlane_b32 s14, v255, 13
	v_cndmask_b32_e32 v3, v1, v3, vcc
	v_lshlrev_b32_e32 v25, 2, v3
	v_xor_b32_e32 v3, 4, v1
	v_cmp_lt_i32_e32 vcc, v3, v2
	v_readlane_b32 s15, v255, 14
	s_mov_b64 s[2:3], 0x1400
	v_cndmask_b32_e32 v3, v1, v3, vcc
	v_lshlrev_b32_e32 v26, 2, v3
	v_xor_b32_e32 v3, 8, v1
	v_cmp_lt_i32_e32 vcc, v3, v2
	s_ashr_i32 s7, s6, 31
	s_mov_b64 s[0:1], 0x1000
	v_cndmask_b32_e32 v3, v1, v3, vcc
	v_lshlrev_b32_e32 v27, 2, v3
	v_xor_b32_e32 v3, 16, v1
	v_cmp_lt_i32_e32 vcc, v3, v2
	v_mov_b32_e32 v30, 0x358637bd
	s_mov_b32 s4, 0xf800000
	v_cndmask_b32_e32 v3, v1, v3, vcc
	v_lshlrev_b32_e32 v28, 2, v3
	v_xor_b32_e32 v3, 32, v1
	v_cmp_lt_i32_e32 vcc, v3, v2
	v_mov_b32_e32 v31, 0x260
	v_readlane_b32 s9, v255, 8
	v_cndmask_b32_e32 v1, v1, v3, vcc
	v_lshlrev_b32_e32 v29, 2, v1
	v_mov_b32_e32 v1, 0
	v_lshl_add_u64 v[12:13], s[14:15], 0, v[0:1]
	v_lshl_add_u64 v[16:17], v[12:13], 0, s[2:3]
	s_mov_b64 s[2:3], 0x1800
	v_lshl_add_u64 v[18:19], v[12:13], 0, s[2:3]
	s_mov_b64 s[2:3], 0x1c00
	v_lshl_add_u64 v[20:21], v[12:13], 0, s[2:3]
	s_lshl_b64 s[2:3], s[6:7], 13
	s_add_u32 s2, s78, s2
	s_addc_u32 s3, s79, s3
	v_lshl_add_u64 v[0:1], s[2:3], 0, v[0:1]
	s_ashr_i32 s75, s74, 31
	v_lshl_add_u64 v[14:15], v[12:13], 0, s[0:1]
	v_lshl_add_u64 v[22:23], v[0:1], 0, s[0:1]
	s_lshl_b64 s[2:3], s[74:75], 13
	v_readlane_b32 s10, v255, 9
	v_readlane_b32 s11, v255, 10
	v_readlane_b32 s12, v255, 11
	v_readlane_b32 s13, v255, 12
	v_readlane_b32 s16, v255, 15
	v_readlane_b32 s17, v255, 16
	v_readlane_b32 s18, v255, 17
	v_readlane_b32 s19, v255, 18
	v_readlane_b32 s20, v255, 19
	v_readlane_b32 s21, v255, 20
	v_readlane_b32 s22, v255, 21
	v_readlane_b32 s23, v255, 22
	global_load_dwordx4 v[132:135], v[12:13], off offset:1024
	global_load_dwordx4 v[136:139], v[12:13], off offset:2048
	global_load_dwordx4 v[140:143], v[12:13], off offset:3072
	global_load_dwordx4 v[144:147], v[14:15], off
	global_load_dwordx4 v[148:151], v[16:17], off
	global_load_dwordx4 v[152:155], v[18:19], off
	global_load_dwordx4 v[156:159], v[20:21], off
.LBB0_1762:
	global_load_dwordx4 v[32:35], v[22:23], off offset:-4096
	global_load_dwordx4 v[8:11], v[22:23], off offset:-3072
	global_load_dwordx4 v[36:39], v[22:23], off offset:-2048
	global_load_dwordx4 v[4:7], v[22:23], off
	global_load_dwordx4 v[40:43], v[22:23], off offset:-1024
	global_load_dwordx4 v[44:47], v[22:23], off offset:1024
	global_load_dwordx4 v[0:3], v[22:23], off offset:3072
	global_load_dwordx4 v[48:51], v[22:23], off offset:2048
	global_load_dwordx4 v[52:55], v[12:13], off
	s_add_i32 s6, s6, s74
	s_cmpk_lt_i32 s6, 0x4000
	s_waitcnt vmcnt(0)
	v_mov_b32_e32 v58, v33
	v_mov_b32_e32 v59, v9
	v_mov_b32_e32 v62, v35
	v_mov_b32_e32 v63, v11
	v_mov_b32_e32 v56, v32
	v_mov_b32_e32 v57, v8
	v_mov_b32_e32 v60, v34
	v_mov_b32_e32 v61, v10
	v_pk_mul_f32 v[64:65], v[38:39], v[38:39]
	v_pk_mul_f32 v[66:67], v[36:37], v[36:37]
	v_pk_mul_f32 v[58:59], v[58:59], v[58:59]
	v_pk_mul_f32 v[62:63], v[62:63], v[62:63]
	v_pk_mov_b32 v[80:81], v[66:67], v[64:65] op_sel:[1,0]
	v_mov_b32_e32 v67, v65
	v_pk_fma_f32 v[56:57], v[56:57], v[56:57], v[58:59]
	v_pk_fma_f32 v[58:59], v[60:61], v[60:61], v[62:63]
	v_mul_f32_e32 v68, v41, v41
	v_mul_f32_e32 v70, v43, v43
	v_pk_add_f32 v[60:61], v[80:81], v[66:67]
	v_pk_add_f32 v[56:57], v[56:57], v[58:59]
	v_mul_f32_e32 v79, v4, v4
	v_mul_f32_e32 v82, v5, v5
	v_mul_f32_e32 v83, v6, v6
	v_mul_f32_e32 v84, v7, v7
	v_pk_fma_f32 v[64:65], v[40:41], v[40:41], v[68:69] op_sel_hi:[1,1,0]
	v_pk_fma_f32 v[68:69], v[42:43], v[42:43], v[70:71] op_sel_hi:[1,1,0]
	v_pk_add_f32 v[58:59], v[60:61], v[60:61] op_sel:[0,1] op_sel_hi:[1,0]
	v_pk_add_f32 v[56:57], v[56:57], v[56:57] op_sel:[0,1] op_sel_hi:[1,0]
	v_pk_mul_f32 v[72:73], v[46:47], v[46:47]
	v_pk_mul_f32 v[74:75], v[44:45], v[44:45]
	v_mov_b32_e32 v65, v83
	v_mov_b32_e32 v69, v84
	v_mov_b32_e32 v59, v82
	v_mov_b32_e32 v57, v79
	v_pk_mov_b32 v[70:71], v[74:75], v[72:73] op_sel:[1,0]
	v_mov_b32_e32 v75, v73
	v_pk_add_f32 v[60:61], v[64:65], v[68:69]
	v_pk_add_f32 v[56:57], v[56:57], v[58:59]
	v_mul_f32_e32 v76, v49, v49
	v_mul_f32_e32 v78, v51, v51
	v_pk_add_f32 v[62:63], v[70:71], v[74:75]
	v_pk_add_f32 v[56:57], v[56:57], v[60:61]
	v_mul_f32_e32 v85, v0, v0
	v_mul_f32_e32 v86, v1, v1
	v_mul_f32_e32 v87, v2, v2
	v_mul_f32_e32 v88, v3, v3
	v_pk_fma_f32 v[72:73], v[48:49], v[48:49], v[76:77] op_sel_hi:[1,1,0]
	v_pk_fma_f32 v[76:77], v[50:51], v[50:51], v[78:79] op_sel_hi:[1,1,0]
	v_pk_add_f32 v[62:63], v[62:63], v[62:63] op_sel:[0,1] op_sel_hi:[1,0]
	v_pk_add_f32 v[56:57], v[56:57], v[56:57] op_sel:[0,1] op_sel_hi:[1,0]
	v_mov_b32_e32 v73, v87
	v_mov_b32_e32 v77, v88
	v_mov_b32_e32 v63, v86
	v_mov_b32_e32 v57, v85
	v_pk_add_f32 v[64:65], v[72:73], v[76:77]
	v_pk_add_f32 v[56:57], v[56:57], v[62:63]
	s_nop 0
	v_pk_add_f32 v[56:57], v[56:57], v[64:65]
	s_nop 0
	v_add_f32_e32 v56, v56, v57
	ds_bpermute_b32 v57, v24, v56
	s_waitcnt lgkmcnt(0)
	v_add_f32_e32 v56, v56, v57
	ds_bpermute_b32 v57, v25, v56
	s_waitcnt lgkmcnt(0)
	v_add_f32_e32 v56, v56, v57
	ds_bpermute_b32 v57, v26, v56
	s_waitcnt lgkmcnt(0)
	v_add_f32_e32 v56, v56, v57
	ds_bpermute_b32 v57, v27, v56
	s_waitcnt lgkmcnt(0)
	v_add_f32_e32 v56, v56, v57
	ds_bpermute_b32 v57, v28, v56
	s_waitcnt lgkmcnt(0)
	v_add_f32_e32 v56, v56, v57
	ds_bpermute_b32 v57, v29, v56
	s_waitcnt lgkmcnt(0)
	v_add_f32_e32 v56, v56, v57
	v_fmamk_f32 v56, v56, 0x3a000000, v30
	v_mul_f32_e32 v57, 0x4f800000, v56
	v_cmp_gt_f32_e32 vcc, s4, v56
	s_nop 1
	v_cndmask_b32_e32 v56, v56, v57, vcc
	v_sqrt_f32_e32 v57, v56
	s_nop 0
	v_add_u32_e32 v58, -1, v57
	v_add_u32_e32 v59, 1, v57
	v_fma_f32 v60, -v58, v57, v56
	v_fma_f32 v61, -v59, v57, v56
	v_cmp_ge_f32_e64 s[0:1], 0, v60
	s_nop 1
	v_cndmask_b32_e64 v57, v57, v58, s[0:1]
	v_cmp_lt_f32_e64 s[0:1], 0, v61
	s_nop 1
	v_cndmask_b32_e64 v57, v57, v59, s[0:1]
	v_mul_f32_e32 v58, 0x37800000, v57
	v_cndmask_b32_e32 v57, v57, v58, vcc
	v_cmp_class_f32_e32 vcc, v56, v31
	s_nop 1
	v_cndmask_b32_e32 v56, v57, v56, vcc
	v_div_scale_f32 v57, s[0:1], v56, v56, 1.0
	v_rcp_f32_e32 v58, v57
	v_div_scale_f32 v59, vcc, 1.0, v56, 1.0
	v_fma_f32 v60, -v57, v58, 1.0
	v_fmac_f32_e32 v58, v60, v58
	v_mul_f32_e32 v60, v59, v58
	v_fma_f32 v61, -v57, v60, v59
	v_fmac_f32_e32 v60, v61, v58
	v_fma_f32 v57, -v57, v60, v59
	v_div_fmas_f32 v57, v57, v58, v60
	v_div_fixup_f32 v56, v57, v56, 1.0
	v_pk_mul_f32 v[32:33], v[32:33], v[56:57] op_sel_hi:[1,0]
	v_pk_mul_f32 v[34:35], v[34:35], v[56:57] op_sel_hi:[1,0]
	v_pk_mul_f32 v[32:33], v[52:53], v[32:33]
	v_pk_mul_f32 v[34:35], v[54:55], v[34:35]
	global_store_dwordx4 v[22:23], v[32:35], off offset:-4096 nt
	s_nop 1
	v_pk_mul_f32 v[10:11], v[10:11], v[56:57] op_sel_hi:[1,0]
	v_pk_mul_f32 v[8:9], v[8:9], v[56:57] op_sel_hi:[1,0]
	v_pk_mul_f32 v[6:7], v[6:7], v[56:57] op_sel_hi:[1,0]
	v_pk_mul_f32 v[4:5], v[4:5], v[56:57] op_sel_hi:[1,0]
	v_pk_mul_f32 v[2:3], v[2:3], v[56:57] op_sel_hi:[1,0]
	v_pk_mul_f32 v[0:1], v[0:1], v[56:57] op_sel_hi:[1,0]
	v_pk_mul_f32 v[8:9], v[132:133], v[8:9]
	v_pk_mul_f32 v[10:11], v[134:135], v[10:11]
	global_store_dwordx4 v[22:23], v[8:11], off offset:-3072 nt
	s_nop 1
	v_pk_mul_f32 v[32:33], v[38:39], v[56:57] op_sel_hi:[1,0]
	v_pk_mul_f32 v[34:35], v[36:37], v[56:57] op_sel_hi:[1,0]
	v_pk_mul_f32 v[10:11], v[138:139], v[32:33]
	v_pk_mul_f32 v[8:9], v[136:137], v[34:35]
	global_store_dwordx4 v[22:23], v[8:11], off offset:-2048 nt
	s_nop 1
	v_pk_mul_f32 v[32:33], v[42:43], v[56:57] op_sel_hi:[1,0]
	v_pk_mul_f32 v[34:35], v[40:41], v[56:57] op_sel_hi:[1,0]
	v_pk_mul_f32 v[10:11], v[142:143], v[32:33]
	v_pk_mul_f32 v[8:9], v[140:141], v[34:35]
	global_store_dwordx4 v[22:23], v[8:11], off offset:-1024 nt
	s_nop 1
	v_pk_mul_f32 v[4:5], v[144:145], v[4:5]
	v_pk_mul_f32 v[6:7], v[146:147], v[6:7]
	global_store_dwordx4 v[22:23], v[4:7], off nt
	s_nop 1
	v_pk_mul_f32 v[8:9], v[46:47], v[56:57] op_sel_hi:[1,0]
	v_pk_mul_f32 v[10:11], v[44:45], v[56:57] op_sel_hi:[1,0]
	v_pk_mul_f32 v[6:7], v[150:151], v[8:9]
	v_pk_mul_f32 v[4:5], v[148:149], v[10:11]
	global_store_dwordx4 v[22:23], v[4:7], off offset:1024 nt
	s_nop 1
	v_pk_mul_f32 v[8:9], v[50:51], v[56:57] op_sel_hi:[1,0]
	v_pk_mul_f32 v[10:11], v[48:49], v[56:57] op_sel_hi:[1,0]
	v_pk_mul_f32 v[6:7], v[8:9], v[154:155]
	v_pk_mul_f32 v[4:5], v[10:11], v[152:153]
	global_store_dwordx4 v[22:23], v[4:7], off offset:2048 nt
	s_nop 1
	v_pk_mul_f32 v[0:1], v[0:1], v[156:157]
	v_pk_mul_f32 v[2:3], v[2:3], v[158:159]
	global_store_dwordx4 v[22:23], v[0:3], off offset:3072 nt
	v_lshl_add_u64 v[22:23], v[22:23], 0, s[2:3]
	s_cbranch_scc1 .LBB0_1762
